# sp5L variant: XGEN poll at K offset 0x200, check at 0x300 (one iteration later than v19)
# speedup vs baseline: 1.0067x; 1.0067x over previous
; __device__ __forceinline__ unsigned xb_ld(unsigned* p)              { return __hip_atomic_load(p, __ATOMIC_RELAXED, __HIP_MEMORY_SCOPE_AGENT); }
; __device__ __forceinline__ unsigned xb_add(unsigned* p, unsigned v) { return __hip_atomic_fetch_add(p, v, __ATOMIC_RELAXED, __HIP_MEMORY_SCOPE_AGENT); }
; #define XB_SPIN(cond, bar) do { unsigned _sp = 0; while (cond) { __builtin_amdgcn_s_sleep(1); \
;     if ((++_sp & 255u) == 0u) { if (xb_ld(&(bar)[XB_TMO])) break; if (_sp > XB_SPIN_CAP) { atomicAdd(&(bar)[XB_TMO], 1u); break; } } } } while (0)
; __device__ __forceinline__ void xcd_barrier(const XcdBarrier& b) {
;     ...
;             else XB_SPIN(xb_ld(&bar[XB_TOPGEN]) == tg, bar);
;             __builtin_amdgcn_fence(__ATOMIC_ACQUIRE, "agent");
;             xb_add(&bar[XB_XGEN(b.x)], 1u);
;             asm volatile("s_waitcnt vmcnt(0)" ::: "memory");
;         } else {
;             XB_SPIN(xb_ld(&bar[XB_XGEN(b.x)]) == gen, bar);
;             __builtin_amdgcn_fence(__ATOMIC_ACQUIRE, "agent");
;             asm volatile("s_waitcnt vmcnt(0)" ::: "memory");
.Lsp5_h:
	s_cmpk_eq_i32 s36, 0x200
	s_cbranch_scc0 .Lsp5_h2
	s_mov_b64 exec, 1
	s_lshl_b32 s98, s33, 8
	s_add_u32 s98, s98, 0x82400
	v_mov_b32_e32 v246, s98
	global_load_dword v247, v246, s[68:69] sc1
	s_mov_b64 exec, -1
	s_branch .Lsp5_back
.Lsp5_h2:
	s_cmpk_eq_i32 s36, 0x300
	s_cbranch_scc0 .Lsp5_back
	s_mov_b64 exec, 1
	s_mov_b32 s98, 0x40000
